# in_even epilogue: both rope-table lookups of a row block issued together (one load latency per block instead of two)
# baseline (speedup 1.0000x reference)
.LBB0_355:
	s_add_u32 s2, s6, 0xfffc0080
	s_addc_u32 s3, s7, -1
	ds_read_b128 v[128:131], v208
	ds_read_b128 v[132:135], v208 offset:1024
	ds_read_b128 v[136:139], v208 offset:2048
	ds_read_b128 v[140:143], v208 offset:3072
	s_cmp_eq_u32 s41, 12
	s_cselect_b32 s9, s1, s3
	s_cselect_b32 s8, s31, s2
	s_cselect_b32 s3, s29, s40
	s_cselect_b32 s2, s38, s39
	s_add_i32 m0, s21, 0xc000
	ds_read_b128 v[144:147], v209
	ds_read_b128 v[148:151], v209 offset:1024
	ds_read_b128 v[152:155], v209 offset:2048
	ds_read_b128 v[156:159], v209 offset:3072
	ds_read_b128 v[180:183], v209 offset:4096
	ds_read_b128 v[184:187], v209 offset:5120
	ds_read_b128 v[188:191], v209 offset:6144
	global_load_lds_dwordx4 v164, s[6:7]
	s_add_i32 m0, s21, 0xe000
	ds_read_b128 v[192:195], v209 offset:7168
	global_load_lds_dwordx4 v166, s[6:7]
	s_waitcnt lgkmcnt(8)
	s_barrier
	s_waitcnt lgkmcnt(0)
	v_mfma_f32_16x16x32_bf16 v[124:127], v[128:131], v[144:147], v[124:127]
	v_mfma_f32_16x16x32_bf16 v[120:123], v[136:139], v[144:147], v[120:123]
	v_mfma_f32_16x16x32_bf16 v[116:119], v[128:131], v[152:155], v[116:119]
	v_mfma_f32_16x16x32_bf16 v[112:115], v[136:139], v[152:155], v[112:115]
	v_mfma_f32_16x16x32_bf16 v[100:103], v[128:131], v[180:183], v[100:103]
	v_mfma_f32_16x16x32_bf16 v[96:99], v[136:139], v[180:183], v[96:99]
	v_mfma_f32_16x16x32_bf16 v[84:87], v[128:131], v[188:191], v[84:87]
	v_mfma_f32_16x16x32_bf16 v[80:83], v[136:139], v[188:191], v[80:83]
	v_mfma_f32_16x16x32_bf16 v[124:127], v[132:135], v[148:151], v[124:127]
	v_mfma_f32_16x16x32_bf16 v[120:123], v[140:143], v[148:151], v[120:123]
	v_mfma_f32_16x16x32_bf16 v[116:119], v[132:135], v[156:159], v[116:119]
	v_mfma_f32_16x16x32_bf16 v[112:115], v[140:143], v[156:159], v[112:115]
	v_mfma_f32_16x16x32_bf16 v[100:103], v[132:135], v[184:187], v[100:103]
	v_mfma_f32_16x16x32_bf16 v[96:99], v[140:143], v[184:187], v[96:99]
	v_mfma_f32_16x16x32_bf16 v[84:87], v[132:135], v[192:195], v[84:87]
	v_mfma_f32_16x16x32_bf16 v[80:83], v[140:143], v[192:195], v[80:83]
	s_barrier
	s_add_u32 s98, s2, 0x80
	s_addc_u32 s99, s3, 0
	s_add_i32 m0, s54, 0x10000
	ds_read_b128 v[196:199], v208 offset:16384
	ds_read_b128 v[200:203], v208 offset:17408
	ds_read_b128 v[210:213], v208 offset:18432
	global_load_lds_dwordx4 v160, s[2:3]
	s_add_i32 m0, s54, 0x12000
	ds_read_b128 v[214:217], v208 offset:19456
	global_load_lds_dwordx4 v162, s[2:3]
	s_barrier
	s_waitcnt lgkmcnt(0)
	v_mfma_f32_16x16x32_bf16 v[108:111], v[196:199], v[144:147], v[108:111]
	v_mfma_f32_16x16x32_bf16 v[104:107], v[210:213], v[144:147], v[104:107]
	v_mfma_f32_16x16x32_bf16 v[92:95], v[196:199], v[152:155], v[92:95]
	v_mfma_f32_16x16x32_bf16 v[88:91], v[210:213], v[152:155], v[88:91]
	v_mfma_f32_16x16x32_bf16 v[76:79], v[196:199], v[180:183], v[76:79]
	v_mfma_f32_16x16x32_bf16 v[72:75], v[210:213], v[180:183], v[72:75]
	v_mfma_f32_16x16x32_bf16 v[68:71], v[196:199], v[188:191], v[68:71]
	v_mfma_f32_16x16x32_bf16 v[64:67], v[210:213], v[188:191], v[64:67]
	v_mfma_f32_16x16x32_bf16 v[108:111], v[200:203], v[148:151], v[108:111]
	v_mfma_f32_16x16x32_bf16 v[104:107], v[214:217], v[148:151], v[104:107]
	v_mfma_f32_16x16x32_bf16 v[92:95], v[200:203], v[156:159], v[92:95]
	v_mfma_f32_16x16x32_bf16 v[88:91], v[214:217], v[156:159], v[88:91]
	v_mfma_f32_16x16x32_bf16 v[76:79], v[200:203], v[184:187], v[76:79]
	v_mfma_f32_16x16x32_bf16 v[72:75], v[214:217], v[184:187], v[72:75]
	v_mfma_f32_16x16x32_bf16 v[68:71], v[200:203], v[192:195], v[68:71]
	v_mfma_f32_16x16x32_bf16 v[64:67], v[214:217], v[192:195], v[64:67]
	s_mov_b32 m0, s21
	s_add_u32 s100, s8, 0x80
	s_addc_u32 s101, s9, 0
	s_barrier
	ds_read_b128 v[144:147], v209 offset:16384
	ds_read_b128 v[148:151], v209 offset:17408
	ds_read_b128 v[152:155], v209 offset:18432
	ds_read_b128 v[156:159], v209 offset:19456
	ds_read_b128 v[180:183], v209 offset:20480
	ds_read_b128 v[184:187], v209 offset:21504
	ds_read_b128 v[188:191], v209 offset:22528
	global_load_lds_dwordx4 v160, s[8:9]
	s_mov_b32 m0, s55
	ds_read_b128 v[192:195], v209 offset:23552
	global_load_lds_dwordx4 v162, s[8:9]
	s_barrier
	s_waitcnt lgkmcnt(0)
	v_mfma_f32_16x16x32_bf16 v[60:63], v[128:131], v[144:147], v[60:63]
	v_mfma_f32_16x16x32_bf16 v[56:59], v[136:139], v[144:147], v[56:59]
	v_mfma_f32_16x16x32_bf16 v[52:55], v[128:131], v[152:155], v[52:55]
	v_mfma_f32_16x16x32_bf16 v[48:51], v[136:139], v[152:155], v[48:51]
	v_mfma_f32_16x16x32_bf16 v[36:39], v[128:131], v[180:183], v[36:39]
	v_mfma_f32_16x16x32_bf16 v[32:35], v[136:139], v[180:183], v[32:35]
	v_mfma_f32_16x16x32_bf16 v[20:23], v[128:131], v[188:191], v[20:23]
	v_mfma_f32_16x16x32_bf16 v[16:19], v[136:139], v[188:191], v[16:19]
	v_mfma_f32_16x16x32_bf16 v[60:63], v[132:135], v[148:151], v[60:63]
	v_mfma_f32_16x16x32_bf16 v[56:59], v[140:143], v[148:151], v[56:59]
	v_mfma_f32_16x16x32_bf16 v[52:55], v[132:135], v[156:159], v[52:55]
	v_mfma_f32_16x16x32_bf16 v[48:51], v[140:143], v[156:159], v[48:51]
	v_mfma_f32_16x16x32_bf16 v[36:39], v[132:135], v[184:187], v[36:39]
	v_mfma_f32_16x16x32_bf16 v[32:35], v[140:143], v[184:187], v[32:35]
	v_mfma_f32_16x16x32_bf16 v[20:23], v[132:135], v[192:195], v[20:23]
	v_mfma_f32_16x16x32_bf16 v[16:19], v[140:143], v[192:195], v[16:19]
	s_barrier
	s_add_i32 m0, s54, 0x14000
	s_add_u32 s64, s2, 0x40000
	s_addc_u32 s65, s3, 0
	global_load_lds_dwordx4 v160, s[64:65]
	s_add_i32 m0, s54, 0x16000
	s_add_u32 s8, s8, 0x40000
	s_addc_u32 s9, s9, 0
	global_load_lds_dwordx4 v162, s[64:65]
	s_waitcnt vmcnt(6)
	s_barrier
	v_mfma_f32_16x16x32_bf16 v[44:47], v[196:199], v[144:147], v[44:47]
	v_mfma_f32_16x16x32_bf16 v[40:43], v[210:213], v[144:147], v[40:43]
	v_mfma_f32_16x16x32_bf16 v[28:31], v[196:199], v[152:155], v[28:31]
	v_mfma_f32_16x16x32_bf16 v[24:27], v[210:213], v[152:155], v[24:27]
	v_mfma_f32_16x16x32_bf16 v[12:15], v[196:199], v[180:183], v[12:15]
	v_mfma_f32_16x16x32_bf16 v[8:11], v[210:213], v[180:183], v[8:11]
	v_mfma_f32_16x16x32_bf16 v[4:7], v[196:199], v[188:191], v[4:7]
	v_mfma_f32_16x16x32_bf16 v[0:3], v[210:213], v[188:191], v[0:3]
	v_mfma_f32_16x16x32_bf16 v[44:47], v[200:203], v[148:151], v[44:47]
	v_mfma_f32_16x16x32_bf16 v[40:43], v[214:217], v[148:151], v[40:43]
	v_mfma_f32_16x16x32_bf16 v[28:31], v[200:203], v[156:159], v[28:31]
	v_mfma_f32_16x16x32_bf16 v[24:27], v[214:217], v[156:159], v[24:27]
	v_mfma_f32_16x16x32_bf16 v[12:15], v[200:203], v[184:187], v[12:15]
	v_mfma_f32_16x16x32_bf16 v[8:11], v[214:217], v[184:187], v[8:11]
	v_mfma_f32_16x16x32_bf16 v[4:7], v[200:203], v[192:195], v[4:7]
	v_mfma_f32_16x16x32_bf16 v[0:3], v[214:217], v[192:195], v[0:3]
	s_barrier
	ds_read_b128 v[128:131], v208 offset:32768
	ds_read_b128 v[132:135], v208 offset:33792
	ds_read_b128 v[136:139], v208 offset:34816
	ds_read_b128 v[140:143], v208 offset:35840
	s_mov_b32 m0, s56
	ds_read_b128 v[144:147], v209 offset:32768
	ds_read_b128 v[148:151], v209 offset:33792
	ds_read_b128 v[152:155], v209 offset:34816
	ds_read_b128 v[156:159], v209 offset:35840
	ds_read_b128 v[180:183], v209 offset:36864
	ds_read_b128 v[184:187], v209 offset:37888
	ds_read_b128 v[188:191], v209 offset:38912
	global_load_lds_dwordx4 v160, s[8:9]
	s_mov_b32 m0, s57
	ds_read_b128 v[192:195], v209 offset:39936
	global_load_lds_dwordx4 v162, s[8:9]
	s_waitcnt lgkmcnt(8)
	s_barrier
	s_waitcnt lgkmcnt(0)
	v_mfma_f32_16x16x32_bf16 v[124:127], v[128:131], v[144:147], v[124:127]
	v_mfma_f32_16x16x32_bf16 v[120:123], v[136:139], v[144:147], v[120:123]
	v_mfma_f32_16x16x32_bf16 v[116:119], v[128:131], v[152:155], v[116:119]
	v_mfma_f32_16x16x32_bf16 v[112:115], v[136:139], v[152:155], v[112:115]
	v_mfma_f32_16x16x32_bf16 v[100:103], v[128:131], v[180:183], v[100:103]
	v_mfma_f32_16x16x32_bf16 v[96:99], v[136:139], v[180:183], v[96:99]
	v_mfma_f32_16x16x32_bf16 v[84:87], v[128:131], v[188:191], v[84:87]
	v_mfma_f32_16x16x32_bf16 v[80:83], v[136:139], v[188:191], v[80:83]
	v_mfma_f32_16x16x32_bf16 v[124:127], v[132:135], v[148:151], v[124:127]
	v_mfma_f32_16x16x32_bf16 v[120:123], v[140:143], v[148:151], v[120:123]
	v_mfma_f32_16x16x32_bf16 v[116:119], v[132:135], v[156:159], v[116:119]
	v_mfma_f32_16x16x32_bf16 v[112:115], v[140:143], v[156:159], v[112:115]
	v_mfma_f32_16x16x32_bf16 v[100:103], v[132:135], v[184:187], v[100:103]
	v_mfma_f32_16x16x32_bf16 v[96:99], v[140:143], v[184:187], v[96:99]
	v_mfma_f32_16x16x32_bf16 v[84:87], v[132:135], v[192:195], v[84:87]
	v_mfma_f32_16x16x32_bf16 v[80:83], v[140:143], v[192:195], v[80:83]
	s_barrier
	s_add_i32 m0, s54, 0x18000
	ds_read_b128 v[196:199], v208 offset:49152
	ds_read_b128 v[200:203], v208 offset:50176
	ds_read_b128 v[210:213], v208 offset:51200
	global_load_lds_dwordx4 v160, s[98:99]
	s_add_i32 m0, s54, 0x1a000
	ds_read_b128 v[214:217], v208 offset:52224
	global_load_lds_dwordx4 v162, s[98:99]
	s_barrier
	s_waitcnt lgkmcnt(0)
	v_mfma_f32_16x16x32_bf16 v[108:111], v[196:199], v[144:147], v[108:111]
	v_mfma_f32_16x16x32_bf16 v[104:107], v[210:213], v[144:147], v[104:107]
	v_mfma_f32_16x16x32_bf16 v[92:95], v[196:199], v[152:155], v[92:95]
	v_mfma_f32_16x16x32_bf16 v[88:91], v[210:213], v[152:155], v[88:91]
	v_mfma_f32_16x16x32_bf16 v[76:79], v[196:199], v[180:183], v[76:79]
	v_mfma_f32_16x16x32_bf16 v[72:75], v[210:213], v[180:183], v[72:75]
	v_mfma_f32_16x16x32_bf16 v[68:71], v[196:199], v[188:191], v[68:71]
	v_mfma_f32_16x16x32_bf16 v[64:67], v[210:213], v[188:191], v[64:67]
	v_mfma_f32_16x16x32_bf16 v[108:111], v[200:203], v[148:151], v[108:111]
	v_mfma_f32_16x16x32_bf16 v[104:107], v[214:217], v[148:151], v[104:107]
	v_mfma_f32_16x16x32_bf16 v[92:95], v[200:203], v[156:159], v[92:95]
	v_mfma_f32_16x16x32_bf16 v[88:91], v[214:217], v[156:159], v[88:91]
	v_mfma_f32_16x16x32_bf16 v[76:79], v[200:203], v[184:187], v[76:79]
	v_mfma_f32_16x16x32_bf16 v[72:75], v[214:217], v[184:187], v[72:75]
	v_mfma_f32_16x16x32_bf16 v[68:71], v[200:203], v[192:195], v[68:71]
	v_mfma_f32_16x16x32_bf16 v[64:67], v[214:217], v[192:195], v[64:67]
	s_mov_b32 m0, s60
	s_barrier
	ds_read_b128 v[144:147], v209 offset:49152
	ds_read_b128 v[148:151], v209 offset:50176
	ds_read_b128 v[152:155], v209 offset:51200
	ds_read_b128 v[156:159], v209 offset:52224
	ds_read_b128 v[180:183], v209 offset:53248
	ds_read_b128 v[184:187], v209 offset:54272
	ds_read_b128 v[188:191], v209 offset:55296
	global_load_lds_dwordx4 v160, s[100:101]
	s_mov_b32 m0, s61
	ds_read_b128 v[192:195], v209 offset:56320
	global_load_lds_dwordx4 v162, s[100:101]
	s_barrier
	s_waitcnt lgkmcnt(0)
	v_mfma_f32_16x16x32_bf16 v[60:63], v[128:131], v[144:147], v[60:63]
	v_mfma_f32_16x16x32_bf16 v[56:59], v[136:139], v[144:147], v[56:59]
	v_mfma_f32_16x16x32_bf16 v[52:55], v[128:131], v[152:155], v[52:55]
	v_mfma_f32_16x16x32_bf16 v[48:51], v[136:139], v[152:155], v[48:51]
	v_mfma_f32_16x16x32_bf16 v[36:39], v[128:131], v[180:183], v[36:39]
	v_mfma_f32_16x16x32_bf16 v[32:35], v[136:139], v[180:183], v[32:35]
	v_mfma_f32_16x16x32_bf16 v[20:23], v[128:131], v[188:191], v[20:23]
	v_mfma_f32_16x16x32_bf16 v[16:19], v[136:139], v[188:191], v[16:19]
	v_mfma_f32_16x16x32_bf16 v[60:63], v[132:135], v[148:151], v[60:63]
	v_mfma_f32_16x16x32_bf16 v[56:59], v[140:143], v[148:151], v[56:59]
	v_mfma_f32_16x16x32_bf16 v[52:55], v[132:135], v[156:159], v[52:55]
	v_mfma_f32_16x16x32_bf16 v[48:51], v[140:143], v[156:159], v[48:51]
	v_mfma_f32_16x16x32_bf16 v[36:39], v[132:135], v[184:187], v[36:39]
	v_mfma_f32_16x16x32_bf16 v[32:35], v[140:143], v[184:187], v[32:35]
	v_mfma_f32_16x16x32_bf16 v[20:23], v[132:135], v[192:195], v[20:23]
	v_mfma_f32_16x16x32_bf16 v[16:19], v[140:143], v[192:195], v[16:19]
	s_barrier
	s_add_i32 m0, s54, 0x1c000
	s_add_u32 s2, s2, 0x40080
	s_addc_u32 s3, s3, 0
	global_load_lds_dwordx4 v160, s[2:3]
	s_add_i32 m0, s54, 0x1e000
	s_add_i32 s41, s41, 2
	global_load_lds_dwordx4 v162, s[2:3]
	s_waitcnt vmcnt(6)
	s_barrier
	v_mfma_f32_16x16x32_bf16 v[44:47], v[196:199], v[144:147], v[44:47]
	v_mfma_f32_16x16x32_bf16 v[40:43], v[210:213], v[144:147], v[40:43]
	v_mfma_f32_16x16x32_bf16 v[28:31], v[196:199], v[152:155], v[28:31]
	v_mfma_f32_16x16x32_bf16 v[24:27], v[210:213], v[152:155], v[24:27]
	v_mfma_f32_16x16x32_bf16 v[12:15], v[196:199], v[180:183], v[12:15]
	v_mfma_f32_16x16x32_bf16 v[8:11], v[210:213], v[180:183], v[8:11]
	v_mfma_f32_16x16x32_bf16 v[4:7], v[196:199], v[188:191], v[4:7]
	v_mfma_f32_16x16x32_bf16 v[0:3], v[210:213], v[188:191], v[0:3]
	v_mfma_f32_16x16x32_bf16 v[44:47], v[200:203], v[148:151], v[44:47]
	v_mfma_f32_16x16x32_bf16 v[40:43], v[214:217], v[148:151], v[40:43]
	v_mfma_f32_16x16x32_bf16 v[28:31], v[200:203], v[156:159], v[28:31]
	v_mfma_f32_16x16x32_bf16 v[24:27], v[214:217], v[156:159], v[24:27]
	v_mfma_f32_16x16x32_bf16 v[12:15], v[200:203], v[184:187], v[12:15]
	v_mfma_f32_16x16x32_bf16 v[8:11], v[214:217], v[184:187], v[8:11]
	v_mfma_f32_16x16x32_bf16 v[4:7], v[200:203], v[192:195], v[4:7]
	v_mfma_f32_16x16x32_bf16 v[0:3], v[214:217], v[192:195], v[0:3]
	s_add_u32 s6, s6, 0x100
	s_addc_u32 s7, s7, 0
	s_add_u32 s39, s39, 0x100
	s_addc_u32 s40, s40, 0
	s_cmp_gt_u32 s41, 13
	s_barrier
	s_cbranch_scc0 .LBB0_355
	s_lshl_b32 s1, s0, 8
	v_mov_b32_e32 v211, v206
	v_mov_b32_e32 v210, v207
	s_add_i32 s1, s1, s59
	s_cmp_lt_i32 s20, 3
	v_add_u32_e32 v180, s1, v211
	s_mov_b64 s[2:3], -1
	s_cbranch_scc0 .LBB0_490
	s_cmp_gt_i32 s0, 15
	s_cselect_b64 s[2:3], -1, 0
	s_cmp_lt_i32 s0, 16
	s_cselect_b64 s[38:39], -1, 0
	s_cmp_eq_u32 s20, 2
	s_cselect_b64 s[8:9], -1, 0
	s_cmp_lg_u32 s20, 2
	s_cselect_b64 s[0:1], -1, 0
	s_and_b64 s[40:41], s[8:9], s[22:23]
	v_lshlrev_b32_e32 v182, 2, v210
	s_mov_b64 s[6:7], -1
	s_and_b64 vcc, exec, s[40:41]
	v_ashrrev_i32_e32 v183, 31, v182
	s_cbranch_vccnz .LBB0_447
	s_and_b64 s[6:7], s[8:9], exec
	s_cselect_b32 s6, s46, s44
	s_cselect_b32 s7, s47, s45
	v_mov_b32_e32 v128, s7
	v_mov_b32_e32 v129, s6
	v_lshl_add_u64 v[128:129], v[182:183], 2, v[128:129]
	global_load_dwordx4 v[140:143], v[128:129], off
	global_load_dwordx4 v[136:139], v[128:129], off offset:64
	global_load_dwordx4 v[132:135], v[128:129], off offset:128
	s_nop 0
	global_load_dwordx4 v[128:131], v[128:129], off offset:192
	v_mul_f32_e32 v144, v125, v125
	v_mul_f32_e32 v145, v127, v127
	v_fmac_f32_e32 v144, v124, v124
	v_fmac_f32_e32 v145, v126, v126
	v_add_f32_e32 v144, v144, v145
	v_mul_f32_e32 v145, v121, v121
	v_mul_f32_e32 v146, v123, v123
	v_fmac_f32_e32 v145, v120, v120
	v_fmac_f32_e32 v146, v122, v122
	v_add_f32_e32 v145, v145, v146
	v_add_f32_e32 v144, v144, v145
	v_mul_f32_e32 v145, v109, v109
	v_mul_f32_e32 v146, v111, v111
	v_fmac_f32_e32 v145, v108, v108
	v_fmac_f32_e32 v146, v110, v110
	v_add_f32_e32 v145, v145, v146
	v_add_f32_e32 v144, v144, v145
	v_mul_f32_e32 v145, v105, v105
	v_mul_f32_e32 v146, v107, v107
	v_fmac_f32_e32 v145, v104, v104
	v_fmac_f32_e32 v146, v106, v106
	v_add_f32_e32 v145, v145, v146
	v_add_f32_e32 v144, v144, v145
	v_mov_b32_e32 v145, v144
	s_nop 1
	v_permlane16_swap_b32_e32 v144, v145
	v_add_f32_e32 v144, v144, v145
	v_mov_b32_e32 v145, v144
	s_nop 1
	v_permlane32_swap_b32_e32 v144, v145
	v_add_f32_e32 v144, v144, v145
	v_fmamk_f32 v144, v144, 0x3c800000, v225
	v_cmp_gt_f32_e32 vcc, s93, v144
	v_mul_f32_e32 v145, 0x4b800000, v144
	v_and_b32_e32 v202, 63, v211
	v_cndmask_b32_e32 v144, v144, v145, vcc
	v_rsq_f32_e32 v144, v144
	v_cndmask_b32_e64 v168, 0, 1, s[2:3]
	v_cmp_ne_u32_e64 s[6:7], 1, v168
	v_lshlrev_b32_e32 v186, 7, v202
	v_mul_f32_e32 v145, 0x45800000, v144
	v_cndmask_b32_e32 v152, v144, v145, vcc
	v_pk_mul_f32 v[144:145], v[124:125], v[152:153] op_sel_hi:[1,0]
	v_pk_mul_f32 v[146:147], v[126:127], v[152:153] op_sel_hi:[1,0]
	v_pk_mul_f32 v[148:149], v[108:109], v[152:153] op_sel_hi:[1,0]
	v_pk_mul_f32 v[150:151], v[110:111], v[152:153] op_sel_hi:[1,0]
	v_pk_mul_f32 v[184:185], v[104:105], v[152:153] op_sel_hi:[1,0]
	s_andn2_b64 vcc, exec, s[2:3]
	s_waitcnt vmcnt(0)
	v_pk_mul_f32 v[158:159], v[142:143], v[146:147]
	v_pk_mul_f32 v[156:157], v[140:141], v[144:145]
	v_pk_mul_f32 v[144:145], v[120:121], v[152:153] op_sel_hi:[1,0]
	v_pk_mul_f32 v[146:147], v[122:123], v[152:153] op_sel_hi:[1,0]
	v_pk_mul_f32 v[152:153], v[106:107], v[152:153] op_sel_hi:[1,0]
	v_pk_mul_f32 v[146:147], v[138:139], v[146:147]
	v_pk_mul_f32 v[144:145], v[136:137], v[144:145]
	v_pk_mul_f32 v[150:151], v[134:135], v[150:151]
	v_pk_mul_f32 v[148:149], v[132:133], v[148:149]
	v_pk_mul_f32 v[154:155], v[130:131], v[152:153]
	v_pk_mul_f32 v[152:153], v[128:129], v[184:185]
	v_lshl_add_u64 v[184:185], v[182:183], 3, s[18:19]
	s_cbranch_vccnz .LBB0_360
	v_lshlrev_b32_e32 v168, 1, v180
	v_and_b32_e32 v168, 0xf80, v168
	v_lshl_add_u64 v[188:189], v[184:185], 0, v[168:169]
	global_load_dwordx4 v[190:193], v[188:189], off offset:16
	global_load_dwordx4 v[194:197], v[188:189], off
	v_mov_b32_e32 v187, v169
	v_lshl_add_u64 v[252:253], v[184:185], 0, v[186:187]
	global_load_dwordx4 v[236:239], v[252:253], off offset:16
	global_load_dwordx4 v[240:243], v[252:253], off
	s_waitcnt vmcnt(2)
	v_mul_f32_e32 v198, v158, v190
	v_mov_b32_e32 v188, v194
	v_mov_b32_e32 v189, v196
	v_mov_b32_e32 v196, v195
	v_mul_f32_e32 v200, v146, v191
	v_mul_f32_e32 v204, v146, v190
	v_mul_f32_e32 v212, v158, v191
	v_mov_b32_e32 v146, v159
	v_mov_b32_e32 v158, v147
	v_pk_mul_f32 v[194:195], v[144:145], v[196:197]
	v_pk_mul_f32 v[144:145], v[144:145], v[188:189]
	v_pk_mul_f32 v[190:191], v[146:147], v[192:193]
	v_pk_mul_f32 v[146:147], v[158:159], v[192:193]
	v_mov_b32_e32 v199, v190
	v_mov_b32_e32 v201, v191
	v_pk_fma_f32 v[190:191], v[156:157], v[188:189], v[194:195] neg_lo:[0,0,1] neg_hi:[0,0,1]
	v_pk_fma_f32 v[144:145], v[156:157], v[196:197], v[144:145]
	v_pk_add_f32 v[188:189], v[198:199], v[200:201] neg_lo:[0,1] neg_hi:[0,1]
	v_mov_b32_e32 v213, v147
	v_mov_b32_e32 v205, v146
	v_pk_add_f32 v[146:147], v[212:213], v[204:205]
	s_waitcnt vmcnt(0)
	v_mov_b64 v[156:157], v[236:237]
	v_mov_b64 v[158:159], v[238:239]
	v_mov_b64 v[192:193], v[240:241]
	v_mov_b64 v[194:195], v[242:243]
	v_mul_f32_e32 v198, v150, v156
	v_mul_f32_e32 v200, v154, v157
	v_mul_f32_e32 v156, v154, v156
	v_mov_b32_e32 v154, v151
	v_mov_b32_e32 v197, v194
	v_mov_b32_e32 v194, v193
	v_mul_f32_e32 v204, v150, v157
	v_pk_mul_f32 v[212:213], v[154:155], v[158:159]
	v_mov_b32_e32 v150, v155
	v_mov_b32_e32 v196, v192
	v_pk_mul_f32 v[192:193], v[152:153], v[194:195]
	v_mov_b32_e32 v199, v212
	v_mov_b32_e32 v201, v213
	v_pk_mul_f32 v[150:151], v[150:151], v[158:159]
	v_pk_mul_f32 v[152:153], v[152:153], v[196:197]
	v_pk_fma_f32 v[192:193], v[148:149], v[196:197], v[192:193] neg_lo:[0,0,1] neg_hi:[0,0,1]
	v_pk_add_f32 v[196:197], v[198:199], v[200:201] neg_lo:[0,1] neg_hi:[0,1]
	v_mov_b32_e32 v205, v151
	v_mov_b32_e32 v157, v150
	v_pk_fma_f32 v[152:153], v[148:149], v[194:195], v[152:153]
	v_pk_add_f32 v[154:155], v[204:205], v[156:157]
	v_mov_b32_e32 v148, v192
	v_mov_b32_e32 v149, v193
	v_mov_b32_e32 v150, v196
	v_mov_b32_e32 v151, v197
	v_mov_b32_e32 v156, v190
	v_mov_b32_e32 v157, v191
	v_mov_b32_e32 v158, v188
	v_mov_b32_e32 v159, v189

.LBB0_369:
	v_mul_f32_e32 v144, v117, v117
	v_mul_f32_e32 v145, v119, v119
	v_fmac_f32_e32 v144, v116, v116
	v_fmac_f32_e32 v145, v118, v118
	v_add_f32_e32 v144, v144, v145
	v_mul_f32_e32 v145, v113, v113
	v_mul_f32_e32 v146, v115, v115
	v_fmac_f32_e32 v145, v112, v112
	v_fmac_f32_e32 v146, v114, v114
	v_add_f32_e32 v145, v145, v146
	v_add_f32_e32 v144, v144, v145
	v_mul_f32_e32 v145, v93, v93
	v_mul_f32_e32 v146, v95, v95
	v_fmac_f32_e32 v145, v92, v92
	v_fmac_f32_e32 v146, v94, v94
	v_add_f32_e32 v145, v145, v146
	v_add_f32_e32 v144, v144, v145
	v_mul_f32_e32 v145, v89, v89
	v_mul_f32_e32 v146, v91, v91
	v_fmac_f32_e32 v145, v88, v88
	v_fmac_f32_e32 v146, v90, v90
	v_add_f32_e32 v145, v145, v146
	v_add_f32_e32 v144, v144, v145
	v_mov_b32_e32 v145, v144
	s_nop 1
	v_permlane16_swap_b32_e32 v144, v145
	v_add_f32_e32 v144, v144, v145
	v_mov_b32_e32 v145, v144
	s_nop 1
	v_permlane32_swap_b32_e32 v144, v145
	v_add_f32_e32 v144, v144, v145
	v_fmamk_f32 v144, v144, 0x3c800000, v225
	v_mul_f32_e32 v145, 0x4b800000, v144
	v_cmp_gt_f32_e32 vcc, s93, v144
	v_add_u32_e32 v190, 16, v180
	s_nop 0
	v_cndmask_b32_e32 v144, v144, v145, vcc
	v_rsq_f32_e32 v144, v144
	v_add_u32_e32 v145, 16, v211
	v_and_b32_e32 v168, 63, v145
	v_mul_f32_e32 v145, 0x45800000, v144
	v_cndmask_b32_e32 v152, v144, v145, vcc
	v_pk_mul_f32 v[144:145], v[116:117], v[152:153] op_sel_hi:[1,0]
	v_pk_mul_f32 v[146:147], v[118:119], v[152:153] op_sel_hi:[1,0]
	v_pk_mul_f32 v[156:157], v[140:141], v[144:145]
	v_pk_mul_f32 v[158:159], v[142:143], v[146:147]
	v_pk_mul_f32 v[144:145], v[112:113], v[152:153] op_sel_hi:[1,0]
	v_pk_mul_f32 v[146:147], v[114:115], v[152:153] op_sel_hi:[1,0]
	v_pk_mul_f32 v[148:149], v[92:93], v[152:153] op_sel_hi:[1,0]
	v_pk_mul_f32 v[150:151], v[94:95], v[152:153] op_sel_hi:[1,0]
	v_pk_mul_f32 v[188:189], v[88:89], v[152:153] op_sel_hi:[1,0]
	v_pk_mul_f32 v[152:153], v[90:91], v[152:153] op_sel_hi:[1,0]
	v_pk_mul_f32 v[146:147], v[138:139], v[146:147]
	v_pk_mul_f32 v[144:145], v[136:137], v[144:145]
	v_pk_mul_f32 v[150:151], v[134:135], v[150:151]
	v_pk_mul_f32 v[148:149], v[132:133], v[148:149]
	v_pk_mul_f32 v[154:155], v[130:131], v[152:153]
	v_pk_mul_f32 v[152:153], v[128:129], v[188:189]
	s_and_b64 vcc, exec, s[6:7]
	v_lshlrev_b32_e32 v188, 7, v168
	s_cbranch_vccnz .LBB0_371
	v_lshlrev_b32_e32 v168, 1, v190
	v_and_b32_e32 v168, 0xf80, v168
	v_lshl_add_u64 v[192:193], v[184:185], 0, v[168:169]
	global_load_dwordx4 v[194:197], v[192:193], off offset:16
	global_load_dwordx4 v[198:201], v[192:193], off
	v_mov_b32_e32 v189, v169
	v_lshl_add_u64 v[252:253], v[184:185], 0, v[188:189]
	global_load_dwordx4 v[236:239], v[252:253], off offset:16
	global_load_dwordx4 v[240:243], v[252:253], off
	s_waitcnt vmcnt(2)
	v_mul_f32_e32 v204, v158, v194
	v_mov_b32_e32 v192, v198
	v_mov_b32_e32 v193, v200
	v_mov_b32_e32 v200, v199
	v_mul_f32_e32 v214, v146, v195
	v_mul_f32_e32 v216, v146, v194
	v_mul_f32_e32 v218, v158, v195
	v_mov_b32_e32 v146, v159
	v_mov_b32_e32 v158, v147
	v_pk_mul_f32 v[198:199], v[144:145], v[200:201]
	v_pk_mul_f32 v[144:145], v[144:145], v[192:193]
	v_pk_mul_f32 v[194:195], v[146:147], v[196:197]
	v_pk_mul_f32 v[146:147], v[158:159], v[196:197]
	v_mov_b32_e32 v205, v194
	v_mov_b32_e32 v215, v195
	v_pk_fma_f32 v[194:195], v[156:157], v[192:193], v[198:199] neg_lo:[0,0,1] neg_hi:[0,0,1]
	v_pk_fma_f32 v[144:145], v[156:157], v[200:201], v[144:145]
	v_pk_add_f32 v[192:193], v[204:205], v[214:215] neg_lo:[0,1] neg_hi:[0,1]
	v_mov_b32_e32 v219, v147
	v_mov_b32_e32 v217, v146
	v_pk_add_f32 v[146:147], v[218:219], v[216:217]
	s_waitcnt vmcnt(0)
	v_mov_b64 v[156:157], v[236:237]
	v_mov_b64 v[158:159], v[238:239]
	v_mov_b64 v[196:197], v[240:241]
	v_mov_b64 v[198:199], v[242:243]
	v_mul_f32_e32 v204, v150, v156
	v_mul_f32_e32 v214, v154, v157
	v_mul_f32_e32 v156, v154, v156
	v_mov_b32_e32 v154, v151
	v_mov_b32_e32 v201, v198
	v_mov_b32_e32 v198, v197
	v_mul_f32_e32 v216, v150, v157
	v_pk_mul_f32 v[218:219], v[154:155], v[158:159]
	v_mov_b32_e32 v150, v155
	v_mov_b32_e32 v200, v196
	v_pk_mul_f32 v[196:197], v[152:153], v[198:199]
	v_mov_b32_e32 v205, v218
	v_mov_b32_e32 v215, v219
	v_pk_mul_f32 v[150:151], v[150:151], v[158:159]
	v_pk_mul_f32 v[152:153], v[152:153], v[200:201]
	v_pk_fma_f32 v[196:197], v[148:149], v[200:201], v[196:197] neg_lo:[0,0,1] neg_hi:[0,0,1]
	v_pk_add_f32 v[200:201], v[204:205], v[214:215] neg_lo:[0,1] neg_hi:[0,1]
	v_mov_b32_e32 v217, v151
	v_mov_b32_e32 v157, v150
	v_pk_fma_f32 v[152:153], v[148:149], v[198:199], v[152:153]
	v_pk_add_f32 v[154:155], v[216:217], v[156:157]
	v_mov_b32_e32 v148, v196
	v_mov_b32_e32 v149, v197
	v_mov_b32_e32 v150, v200
	v_mov_b32_e32 v151, v201
	v_mov_b32_e32 v156, v194
	v_mov_b32_e32 v157, v195
	v_mov_b32_e32 v158, v192
	v_mov_b32_e32 v159, v193

.LBB0_380:
	v_mul_f32_e32 v144, v101, v101
	v_mul_f32_e32 v145, v103, v103
	v_fmac_f32_e32 v144, v100, v100
	v_fmac_f32_e32 v145, v102, v102
	v_add_f32_e32 v144, v144, v145
	v_mul_f32_e32 v145, v97, v97
	v_mul_f32_e32 v146, v99, v99
	v_fmac_f32_e32 v145, v96, v96
	v_fmac_f32_e32 v146, v98, v98
	v_add_f32_e32 v145, v145, v146
	v_add_f32_e32 v144, v144, v145
	v_mul_f32_e32 v145, v77, v77
	v_mul_f32_e32 v146, v79, v79
	v_fmac_f32_e32 v145, v76, v76
	v_fmac_f32_e32 v146, v78, v78
	v_add_f32_e32 v145, v145, v146
	v_add_f32_e32 v144, v144, v145
	v_mul_f32_e32 v145, v73, v73
	v_mul_f32_e32 v146, v75, v75
	v_fmac_f32_e32 v145, v72, v72
	v_fmac_f32_e32 v146, v74, v74
	v_add_f32_e32 v145, v145, v146
	v_add_f32_e32 v144, v144, v145
	v_mov_b32_e32 v145, v144
	s_nop 1
	v_permlane16_swap_b32_e32 v144, v145
	v_add_f32_e32 v144, v144, v145
	v_mov_b32_e32 v145, v144
	s_nop 1
	v_permlane32_swap_b32_e32 v144, v145
	v_add_f32_e32 v144, v144, v145
	v_fmamk_f32 v144, v144, 0x3c800000, v225
	v_mul_f32_e32 v145, 0x4b800000, v144
	v_cmp_gt_f32_e32 vcc, s93, v144
	v_xor_b32_e32 v168, 32, v202
	v_add_u32_e32 v192, 32, v180
	v_cndmask_b32_e32 v144, v144, v145, vcc
	v_rsq_f32_e32 v144, v144
	s_nop 0
	v_mul_f32_e32 v145, 0x45800000, v144
	v_cndmask_b32_e32 v152, v144, v145, vcc
	v_pk_mul_f32 v[144:145], v[100:101], v[152:153] op_sel_hi:[1,0]
	v_pk_mul_f32 v[146:147], v[102:103], v[152:153] op_sel_hi:[1,0]
	v_pk_mul_f32 v[156:157], v[140:141], v[144:145]
	v_pk_mul_f32 v[158:159], v[142:143], v[146:147]
	v_pk_mul_f32 v[144:145], v[96:97], v[152:153] op_sel_hi:[1,0]
	v_pk_mul_f32 v[146:147], v[98:99], v[152:153] op_sel_hi:[1,0]
	v_pk_mul_f32 v[148:149], v[76:77], v[152:153] op_sel_hi:[1,0]
	v_pk_mul_f32 v[150:151], v[78:79], v[152:153] op_sel_hi:[1,0]
	v_pk_mul_f32 v[190:191], v[72:73], v[152:153] op_sel_hi:[1,0]
	v_pk_mul_f32 v[152:153], v[74:75], v[152:153] op_sel_hi:[1,0]
	v_pk_mul_f32 v[146:147], v[138:139], v[146:147]
	v_pk_mul_f32 v[144:145], v[136:137], v[144:145]
	v_pk_mul_f32 v[150:151], v[134:135], v[150:151]
	v_pk_mul_f32 v[148:149], v[132:133], v[148:149]
	v_pk_mul_f32 v[154:155], v[130:131], v[152:153]
	v_pk_mul_f32 v[152:153], v[128:129], v[190:191]
	s_and_b64 vcc, exec, s[6:7]
	v_lshlrev_b32_e32 v190, 7, v168
	s_cbranch_vccnz .LBB0_382
	v_lshlrev_b32_e32 v168, 1, v192
	v_and_b32_e32 v168, 0xf80, v168
	v_lshl_add_u64 v[194:195], v[184:185], 0, v[168:169]
	global_load_dwordx4 v[196:199], v[194:195], off offset:16
	global_load_dwordx4 v[200:203], v[194:195], off
	v_mov_b32_e32 v191, v169
	v_lshl_add_u64 v[252:253], v[184:185], 0, v[190:191]
	global_load_dwordx4 v[236:239], v[252:253], off offset:16
	global_load_dwordx4 v[240:243], v[252:253], off
	s_waitcnt vmcnt(2)
	v_mul_f32_e32 v204, v158, v196
	v_mov_b32_e32 v194, v200
	v_mov_b32_e32 v195, v202
	v_mov_b32_e32 v202, v201
	v_mul_f32_e32 v214, v146, v197
	v_mul_f32_e32 v216, v146, v196
	v_mul_f32_e32 v218, v158, v197
	v_mov_b32_e32 v146, v159
	v_mov_b32_e32 v158, v147
	v_pk_mul_f32 v[200:201], v[144:145], v[202:203]
	v_pk_mul_f32 v[144:145], v[144:145], v[194:195]
	v_pk_mul_f32 v[196:197], v[146:147], v[198:199]
	v_pk_mul_f32 v[146:147], v[158:159], v[198:199]
	v_mov_b32_e32 v205, v196
	v_mov_b32_e32 v215, v197
	v_pk_fma_f32 v[196:197], v[156:157], v[194:195], v[200:201] neg_lo:[0,0,1] neg_hi:[0,0,1]
	v_pk_fma_f32 v[144:145], v[156:157], v[202:203], v[144:145]
	v_pk_add_f32 v[194:195], v[204:205], v[214:215] neg_lo:[0,1] neg_hi:[0,1]
	v_mov_b32_e32 v219, v147
	v_mov_b32_e32 v217, v146
	v_pk_add_f32 v[146:147], v[218:219], v[216:217]
	s_waitcnt vmcnt(0)
	v_mov_b64 v[156:157], v[236:237]
	v_mov_b64 v[158:159], v[238:239]
	v_mov_b64 v[198:199], v[240:241]
	v_mov_b64 v[200:201], v[242:243]
	v_mul_f32_e32 v204, v150, v156
	v_mul_f32_e32 v214, v154, v157
	v_mul_f32_e32 v156, v154, v156
	v_mov_b32_e32 v154, v151
	v_mov_b32_e32 v203, v200
	v_mov_b32_e32 v200, v199
	v_mul_f32_e32 v216, v150, v157
	v_pk_mul_f32 v[218:219], v[154:155], v[158:159]
	v_mov_b32_e32 v150, v155
	v_mov_b32_e32 v202, v198
	v_pk_mul_f32 v[198:199], v[152:153], v[200:201]
	v_mov_b32_e32 v205, v218
	v_mov_b32_e32 v215, v219
	v_pk_mul_f32 v[150:151], v[150:151], v[158:159]
	v_pk_mul_f32 v[152:153], v[152:153], v[202:203]
	v_pk_fma_f32 v[198:199], v[148:149], v[202:203], v[198:199] neg_lo:[0,0,1] neg_hi:[0,0,1]
	v_pk_add_f32 v[202:203], v[204:205], v[214:215] neg_lo:[0,1] neg_hi:[0,1]
	v_mov_b32_e32 v217, v151
	v_mov_b32_e32 v157, v150
	v_pk_fma_f32 v[152:153], v[148:149], v[200:201], v[152:153]
	v_pk_add_f32 v[154:155], v[216:217], v[156:157]
	v_mov_b32_e32 v148, v198
	v_mov_b32_e32 v149, v199
	v_mov_b32_e32 v150, v202
	v_mov_b32_e32 v151, v203
	v_mov_b32_e32 v156, v196
	v_mov_b32_e32 v157, v197
	v_mov_b32_e32 v158, v194
	v_mov_b32_e32 v159, v195

.LBB0_391:
	v_mul_f32_e32 v144, v85, v85
	v_mul_f32_e32 v145, v87, v87
	v_fmac_f32_e32 v144, v84, v84
	v_fmac_f32_e32 v145, v86, v86
	v_add_f32_e32 v144, v144, v145
	v_mul_f32_e32 v145, v81, v81
	v_mul_f32_e32 v146, v83, v83
	v_fmac_f32_e32 v145, v80, v80
	v_fmac_f32_e32 v146, v82, v82
	v_add_f32_e32 v145, v145, v146
	v_add_f32_e32 v144, v144, v145
	v_mul_f32_e32 v145, v69, v69
	v_mul_f32_e32 v146, v71, v71
	v_fmac_f32_e32 v145, v68, v68
	v_fmac_f32_e32 v146, v70, v70
	v_add_f32_e32 v145, v145, v146
	v_add_f32_e32 v144, v144, v145
	v_mul_f32_e32 v145, v65, v65
	v_mul_f32_e32 v146, v67, v67
	v_fmac_f32_e32 v145, v64, v64
	v_fmac_f32_e32 v146, v66, v66
	v_add_f32_e32 v145, v145, v146
	v_add_f32_e32 v144, v144, v145
	v_mov_b32_e32 v145, v144
	s_nop 1
	v_permlane16_swap_b32_e32 v144, v145
	v_add_f32_e32 v144, v144, v145
	v_mov_b32_e32 v145, v144
	s_nop 1
	v_permlane32_swap_b32_e32 v144, v145
	v_add_f32_e32 v144, v144, v145
	v_fmamk_f32 v144, v144, 0x3c800000, v225
	v_mul_f32_e32 v145, 0x4b800000, v144
	v_cmp_gt_f32_e32 vcc, s93, v144
	v_add_u32_e32 v194, 48, v180
	s_nop 0
	v_cndmask_b32_e32 v144, v144, v145, vcc
	v_rsq_f32_e32 v144, v144
	v_add_u32_e32 v145, 48, v211
	v_and_b32_e32 v168, 63, v145
	v_mul_f32_e32 v145, 0x45800000, v144
	v_cndmask_b32_e32 v152, v144, v145, vcc
	v_pk_mul_f32 v[144:145], v[84:85], v[152:153] op_sel_hi:[1,0]
	v_pk_mul_f32 v[146:147], v[86:87], v[152:153] op_sel_hi:[1,0]
	v_pk_mul_f32 v[156:157], v[140:141], v[144:145]
	v_pk_mul_f32 v[158:159], v[142:143], v[146:147]
	v_pk_mul_f32 v[144:145], v[80:81], v[152:153] op_sel_hi:[1,0]
	v_pk_mul_f32 v[146:147], v[82:83], v[152:153] op_sel_hi:[1,0]
	v_pk_mul_f32 v[148:149], v[68:69], v[152:153] op_sel_hi:[1,0]
	v_pk_mul_f32 v[150:151], v[70:71], v[152:153] op_sel_hi:[1,0]
	v_pk_mul_f32 v[192:193], v[64:65], v[152:153] op_sel_hi:[1,0]
	v_pk_mul_f32 v[152:153], v[66:67], v[152:153] op_sel_hi:[1,0]
	v_pk_mul_f32 v[146:147], v[138:139], v[146:147]
	v_pk_mul_f32 v[144:145], v[136:137], v[144:145]
	v_pk_mul_f32 v[150:151], v[134:135], v[150:151]
	v_pk_mul_f32 v[148:149], v[132:133], v[148:149]
	v_pk_mul_f32 v[154:155], v[130:131], v[152:153]
	v_pk_mul_f32 v[152:153], v[128:129], v[192:193]
	s_and_b64 vcc, exec, s[6:7]
	v_lshlrev_b32_e32 v192, 7, v168
	s_cbranch_vccnz .LBB0_393
	v_lshlrev_b32_e32 v168, 1, v194
	v_and_b32_e32 v168, 0xf80, v168
	v_lshl_add_u64 v[196:197], v[184:185], 0, v[168:169]
	global_load_dwordx4 v[198:201], v[196:197], off offset:16
	global_load_dwordx4 v[202:205], v[196:197], off
	v_mov_b32_e32 v193, v169
	v_lshl_add_u64 v[252:253], v[184:185], 0, v[192:193]
	global_load_dwordx4 v[236:239], v[252:253], off offset:16
	global_load_dwordx4 v[240:243], v[252:253], off
	s_waitcnt vmcnt(2)
	v_mul_f32_e32 v214, v158, v198
	v_mov_b32_e32 v196, v202
	v_mov_b32_e32 v197, v204
	v_mov_b32_e32 v204, v203
	v_mul_f32_e32 v216, v146, v199
	v_mul_f32_e32 v218, v146, v198
	v_mul_f32_e32 v220, v158, v199
	v_mov_b32_e32 v146, v159
	v_mov_b32_e32 v158, v147
	v_pk_mul_f32 v[202:203], v[144:145], v[204:205]
	v_pk_mul_f32 v[144:145], v[144:145], v[196:197]
	v_pk_mul_f32 v[198:199], v[146:147], v[200:201]
	v_pk_mul_f32 v[146:147], v[158:159], v[200:201]
	v_mov_b32_e32 v215, v198
	v_mov_b32_e32 v217, v199
	v_pk_fma_f32 v[198:199], v[156:157], v[196:197], v[202:203] neg_lo:[0,0,1] neg_hi:[0,0,1]
	v_pk_fma_f32 v[144:145], v[156:157], v[204:205], v[144:145]
	v_pk_add_f32 v[196:197], v[214:215], v[216:217] neg_lo:[0,1] neg_hi:[0,1]
	v_mov_b32_e32 v221, v147
	v_mov_b32_e32 v219, v146
	v_pk_add_f32 v[146:147], v[220:221], v[218:219]
	s_waitcnt vmcnt(0)
	v_mov_b64 v[156:157], v[236:237]
	v_mov_b64 v[158:159], v[238:239]
	v_mov_b64 v[200:201], v[240:241]
	v_mov_b64 v[202:203], v[242:243]
	v_mul_f32_e32 v214, v150, v156
	v_mul_f32_e32 v216, v154, v157
	v_mul_f32_e32 v156, v154, v156
	v_mov_b32_e32 v154, v151
	v_mov_b32_e32 v205, v202
	v_mov_b32_e32 v202, v201
	v_mul_f32_e32 v218, v150, v157
	v_pk_mul_f32 v[220:221], v[154:155], v[158:159]
	v_mov_b32_e32 v150, v155
	v_mov_b32_e32 v204, v200
	v_pk_mul_f32 v[200:201], v[152:153], v[202:203]
	v_mov_b32_e32 v215, v220
	v_mov_b32_e32 v217, v221
	v_pk_mul_f32 v[150:151], v[150:151], v[158:159]
	v_pk_mul_f32 v[152:153], v[152:153], v[204:205]
	v_pk_fma_f32 v[200:201], v[148:149], v[204:205], v[200:201] neg_lo:[0,0,1] neg_hi:[0,0,1]
	v_pk_add_f32 v[204:205], v[214:215], v[216:217] neg_lo:[0,1] neg_hi:[0,1]
	v_mov_b32_e32 v219, v151
	v_mov_b32_e32 v157, v150
	v_pk_fma_f32 v[152:153], v[148:149], v[202:203], v[152:153]
	v_pk_add_f32 v[154:155], v[218:219], v[156:157]
	v_mov_b32_e32 v148, v200
	v_mov_b32_e32 v149, v201
	v_mov_b32_e32 v150, v204
	v_mov_b32_e32 v151, v205
	v_mov_b32_e32 v156, v198
	v_mov_b32_e32 v157, v199
	v_mov_b32_e32 v158, v196
	v_mov_b32_e32 v159, v197

.LBB0_402:
	v_mul_f32_e32 v144, v61, v61
	v_mul_f32_e32 v145, v63, v63
	v_fmac_f32_e32 v144, v60, v60
	v_fmac_f32_e32 v145, v62, v62
	v_add_f32_e32 v144, v144, v145
	v_mul_f32_e32 v145, v57, v57
	v_mul_f32_e32 v146, v59, v59
	v_fmac_f32_e32 v145, v56, v56
	v_fmac_f32_e32 v146, v58, v58
	v_add_f32_e32 v145, v145, v146
	v_add_f32_e32 v144, v144, v145
	v_mul_f32_e32 v145, v45, v45
	v_mul_f32_e32 v146, v47, v47
	v_fmac_f32_e32 v145, v44, v44
	v_fmac_f32_e32 v146, v46, v46
	v_add_f32_e32 v145, v145, v146
	v_add_f32_e32 v144, v144, v145
	v_mul_f32_e32 v145, v41, v41
	v_mul_f32_e32 v146, v43, v43
	v_fmac_f32_e32 v145, v40, v40
	v_fmac_f32_e32 v146, v42, v42
	v_add_f32_e32 v145, v145, v146
	v_add_f32_e32 v144, v144, v145
	v_mov_b32_e32 v145, v144
	s_nop 1
	v_permlane16_swap_b32_e32 v144, v145
	v_add_f32_e32 v144, v144, v145
	v_mov_b32_e32 v145, v144
	s_nop 1
	v_permlane32_swap_b32_e32 v144, v145
	v_add_f32_e32 v144, v144, v145
	v_fmamk_f32 v144, v144, 0x3c800000, v225
	v_mul_f32_e32 v145, 0x4b800000, v144
	v_cmp_gt_f32_e32 vcc, s93, v144
	v_add_u32_e32 v194, 0x80, v180
	s_nop 0
	v_cndmask_b32_e32 v144, v144, v145, vcc
	v_rsq_f32_e32 v144, v144
	s_nop 0
	v_mul_f32_e32 v145, 0x45800000, v144
	v_cndmask_b32_e32 v152, v144, v145, vcc
	v_pk_mul_f32 v[144:145], v[60:61], v[152:153] op_sel_hi:[1,0]
	v_pk_mul_f32 v[146:147], v[62:63], v[152:153] op_sel_hi:[1,0]
	v_pk_mul_f32 v[156:157], v[140:141], v[144:145]
	v_pk_mul_f32 v[158:159], v[142:143], v[146:147]
	v_pk_mul_f32 v[144:145], v[56:57], v[152:153] op_sel_hi:[1,0]
	v_pk_mul_f32 v[146:147], v[58:59], v[152:153] op_sel_hi:[1,0]
	v_pk_mul_f32 v[148:149], v[44:45], v[152:153] op_sel_hi:[1,0]
	v_pk_mul_f32 v[150:151], v[46:47], v[152:153] op_sel_hi:[1,0]
	v_pk_mul_f32 v[196:197], v[40:41], v[152:153] op_sel_hi:[1,0]
	v_pk_mul_f32 v[152:153], v[42:43], v[152:153] op_sel_hi:[1,0]
	v_pk_mul_f32 v[146:147], v[138:139], v[146:147]
	v_pk_mul_f32 v[144:145], v[136:137], v[144:145]
	v_pk_mul_f32 v[150:151], v[134:135], v[150:151]
	v_pk_mul_f32 v[148:149], v[132:133], v[148:149]
	v_pk_mul_f32 v[154:155], v[130:131], v[152:153]
	s_and_b64 vcc, exec, s[6:7]
	v_pk_mul_f32 v[152:153], v[128:129], v[196:197]
	s_cbranch_vccnz .LBB0_404
	v_lshlrev_b32_e32 v168, 1, v194
	v_and_b32_e32 v168, 0xf80, v168
	v_lshl_add_u64 v[196:197], v[184:185], 0, v[168:169]
	global_load_dwordx4 v[198:201], v[196:197], off offset:16
	global_load_dwordx4 v[202:205], v[196:197], off
	v_mov_b32_e32 v187, v169
	v_lshl_add_u64 v[186:187], v[184:185], 0, v[186:187]
	global_load_dwordx4 v[236:239], v[186:187], off offset:16
	global_load_dwordx4 v[240:243], v[186:187], off
	s_waitcnt vmcnt(2)
	v_mul_f32_e32 v216, v146, v199
	v_mov_b32_e32 v196, v202
	v_mov_b32_e32 v197, v204
	v_mov_b32_e32 v204, v203
	v_mul_f32_e32 v218, v146, v198
	v_mov_b32_e32 v146, v159
	v_pk_mul_f32 v[202:203], v[144:145], v[204:205]
	v_pk_mul_f32 v[144:145], v[144:145], v[196:197]
	v_mul_f32_e32 v214, v158, v198
	v_mul_f32_e32 v220, v158, v199
	v_pk_mul_f32 v[198:199], v[146:147], v[200:201]
	v_mov_b32_e32 v158, v147
	v_mov_b32_e32 v215, v198
	v_mov_b32_e32 v217, v199
	v_pk_fma_f32 v[198:199], v[156:157], v[196:197], v[202:203] neg_lo:[0,0,1] neg_hi:[0,0,1]
	v_pk_mul_f32 v[146:147], v[158:159], v[200:201]
	v_pk_fma_f32 v[144:145], v[156:157], v[204:205], v[144:145]
	v_pk_add_f32 v[196:197], v[214:215], v[216:217] neg_lo:[0,1] neg_hi:[0,1]
	v_mov_b32_e32 v221, v147
	v_mov_b32_e32 v219, v146
	v_pk_add_f32 v[146:147], v[220:221], v[218:219]
	s_waitcnt vmcnt(0)
	v_mov_b64 v[156:157], v[236:237]
	v_mov_b64 v[158:159], v[238:239]
	v_mov_b64 v[200:201], v[240:241]
	v_mov_b64 v[202:203], v[242:243]
	v_mul_f32_e32 v204, v150, v156
	v_mul_f32_e32 v214, v154, v157
	v_mul_f32_e32 v156, v154, v156
	v_mov_b32_e32 v154, v151
	v_mov_b32_e32 v187, v202
	v_mov_b32_e32 v202, v201
	v_mul_f32_e32 v216, v150, v157
	v_pk_mul_f32 v[218:219], v[154:155], v[158:159]
	v_mov_b32_e32 v150, v155
	v_mov_b32_e32 v186, v200
	v_pk_mul_f32 v[200:201], v[152:153], v[202:203]
	v_mov_b32_e32 v205, v218
	v_mov_b32_e32 v215, v219
	v_pk_mul_f32 v[150:151], v[150:151], v[158:159]
	v_pk_mul_f32 v[152:153], v[152:153], v[186:187]
	v_pk_fma_f32 v[186:187], v[148:149], v[186:187], v[200:201] neg_lo:[0,0,1] neg_hi:[0,0,1]
	v_pk_add_f32 v[200:201], v[204:205], v[214:215] neg_lo:[0,1] neg_hi:[0,1]
	v_mov_b32_e32 v217, v151
	v_mov_b32_e32 v157, v150
	v_pk_fma_f32 v[152:153], v[148:149], v[202:203], v[152:153]
	v_pk_add_f32 v[154:155], v[216:217], v[156:157]
	v_mov_b32_e32 v148, v186
	v_mov_b32_e32 v149, v187
	v_mov_b32_e32 v150, v200
	v_mov_b32_e32 v151, v201
	v_mov_b32_e32 v156, v198
	v_mov_b32_e32 v157, v199
	v_mov_b32_e32 v158, v196
	v_mov_b32_e32 v159, v197

.LBB0_413:
	v_mul_f32_e32 v144, v53, v53
	v_mul_f32_e32 v145, v55, v55
	v_fmac_f32_e32 v144, v52, v52
	v_fmac_f32_e32 v145, v54, v54
	v_add_f32_e32 v144, v144, v145
	v_mul_f32_e32 v145, v49, v49
	v_mul_f32_e32 v146, v51, v51
	v_fmac_f32_e32 v145, v48, v48
	v_fmac_f32_e32 v146, v50, v50
	v_add_f32_e32 v145, v145, v146
	v_add_f32_e32 v144, v144, v145
	v_mul_f32_e32 v145, v29, v29
	v_mul_f32_e32 v146, v31, v31
	v_fmac_f32_e32 v145, v28, v28
	v_fmac_f32_e32 v146, v30, v30
	v_add_f32_e32 v145, v145, v146
	v_add_f32_e32 v144, v144, v145
	v_mul_f32_e32 v145, v25, v25
	v_mul_f32_e32 v146, v27, v27
	v_fmac_f32_e32 v145, v24, v24
	v_fmac_f32_e32 v146, v26, v26
	v_add_f32_e32 v145, v145, v146
	v_add_f32_e32 v144, v144, v145
	v_mov_b32_e32 v145, v144
	s_nop 1
	v_permlane16_swap_b32_e32 v144, v145
	v_add_f32_e32 v144, v144, v145
	v_mov_b32_e32 v145, v144
	s_nop 1
	v_permlane32_swap_b32_e32 v144, v145
	v_add_f32_e32 v144, v144, v145
	v_fmamk_f32 v144, v144, 0x3c800000, v225
	v_mul_f32_e32 v145, 0x4b800000, v144
	v_cmp_gt_f32_e32 vcc, s93, v144
	s_nop 1
	v_cndmask_b32_e32 v144, v144, v145, vcc
	v_rsq_f32_e32 v144, v144
	s_nop 0
	v_mul_f32_e32 v145, 0x45800000, v144
	v_cndmask_b32_e32 v152, v144, v145, vcc
	v_pk_mul_f32 v[144:145], v[52:53], v[152:153] op_sel_hi:[1,0]
	v_pk_mul_f32 v[146:147], v[54:55], v[152:153] op_sel_hi:[1,0]
	v_pk_mul_f32 v[156:157], v[140:141], v[144:145]
	v_pk_mul_f32 v[158:159], v[142:143], v[146:147]
	v_pk_mul_f32 v[144:145], v[48:49], v[152:153] op_sel_hi:[1,0]
	v_pk_mul_f32 v[146:147], v[50:51], v[152:153] op_sel_hi:[1,0]
	v_pk_mul_f32 v[148:149], v[28:29], v[152:153] op_sel_hi:[1,0]
	v_pk_mul_f32 v[150:151], v[30:31], v[152:153] op_sel_hi:[1,0]
	v_pk_mul_f32 v[186:187], v[24:25], v[152:153] op_sel_hi:[1,0]
	v_pk_mul_f32 v[152:153], v[26:27], v[152:153] op_sel_hi:[1,0]
	v_pk_mul_f32 v[146:147], v[138:139], v[146:147]
	v_pk_mul_f32 v[144:145], v[136:137], v[144:145]
	v_pk_mul_f32 v[150:151], v[134:135], v[150:151]
	v_pk_mul_f32 v[148:149], v[132:133], v[148:149]
	v_pk_mul_f32 v[154:155], v[130:131], v[152:153]
	v_pk_mul_f32 v[152:153], v[128:129], v[186:187]
	s_and_b64 vcc, exec, s[6:7]
	v_add_u32_e32 v186, 0x90, v180
	s_cbranch_vccnz .LBB0_415
	v_lshlrev_b32_e32 v168, 1, v186
	v_and_b32_e32 v168, 0xf80, v168
	v_lshl_add_u64 v[194:195], v[184:185], 0, v[168:169]
	global_load_dwordx4 v[196:199], v[194:195], off offset:16
	global_load_dwordx4 v[200:203], v[194:195], off
	v_mov_b32_e32 v189, v169
	v_lshl_add_u64 v[188:189], v[184:185], 0, v[188:189]
	global_load_dwordx4 v[236:239], v[188:189], off offset:16
	global_load_dwordx4 v[240:243], v[188:189], off
	s_waitcnt vmcnt(2)
	v_mul_f32_e32 v214, v146, v197
	v_mov_b32_e32 v194, v200
	v_mov_b32_e32 v195, v202
	v_mov_b32_e32 v202, v201
	v_mul_f32_e32 v216, v146, v196
	v_mov_b32_e32 v146, v159
	v_pk_mul_f32 v[200:201], v[144:145], v[202:203]
	v_pk_mul_f32 v[144:145], v[144:145], v[194:195]
	v_mul_f32_e32 v204, v158, v196
	v_mul_f32_e32 v218, v158, v197
	v_pk_mul_f32 v[196:197], v[146:147], v[198:199]
	v_mov_b32_e32 v158, v147
	v_mov_b32_e32 v205, v196
	v_mov_b32_e32 v215, v197
	v_pk_fma_f32 v[196:197], v[156:157], v[194:195], v[200:201] neg_lo:[0,0,1] neg_hi:[0,0,1]
	v_pk_mul_f32 v[146:147], v[158:159], v[198:199]
	v_pk_fma_f32 v[144:145], v[156:157], v[202:203], v[144:145]
	v_pk_add_f32 v[194:195], v[204:205], v[214:215] neg_lo:[0,1] neg_hi:[0,1]
	v_mov_b32_e32 v219, v147
	v_mov_b32_e32 v217, v146
	v_pk_add_f32 v[146:147], v[218:219], v[216:217]
	s_waitcnt vmcnt(0)
	v_mov_b64 v[156:157], v[236:237]
	v_mov_b64 v[158:159], v[238:239]
	v_mov_b64 v[198:199], v[240:241]
	v_mov_b64 v[200:201], v[242:243]
	v_mul_f32_e32 v202, v150, v156
	v_mul_f32_e32 v204, v154, v157
	v_mul_f32_e32 v156, v154, v156
	v_mov_b32_e32 v154, v151
	v_mov_b32_e32 v189, v200
	v_mov_b32_e32 v200, v199
	v_mul_f32_e32 v214, v150, v157
	v_pk_mul_f32 v[216:217], v[154:155], v[158:159]
	v_mov_b32_e32 v150, v155
	v_mov_b32_e32 v188, v198
	v_pk_mul_f32 v[198:199], v[152:153], v[200:201]
	v_mov_b32_e32 v203, v216
	v_mov_b32_e32 v205, v217
	v_pk_mul_f32 v[150:151], v[150:151], v[158:159]
	v_pk_mul_f32 v[152:153], v[152:153], v[188:189]
	v_pk_fma_f32 v[188:189], v[148:149], v[188:189], v[198:199] neg_lo:[0,0,1] neg_hi:[0,0,1]
	v_pk_add_f32 v[198:199], v[202:203], v[204:205] neg_lo:[0,1] neg_hi:[0,1]
	v_mov_b32_e32 v215, v151
	v_mov_b32_e32 v157, v150
	v_pk_fma_f32 v[152:153], v[148:149], v[200:201], v[152:153]
	v_pk_add_f32 v[154:155], v[214:215], v[156:157]
	v_mov_b32_e32 v148, v188
	v_mov_b32_e32 v149, v189
	v_mov_b32_e32 v150, v198
	v_mov_b32_e32 v151, v199
	v_mov_b32_e32 v156, v196
	v_mov_b32_e32 v157, v197
	v_mov_b32_e32 v158, v194
	v_mov_b32_e32 v159, v195

.LBB0_424:
	v_mul_f32_e32 v144, v37, v37
	v_mul_f32_e32 v145, v39, v39
	v_fmac_f32_e32 v144, v36, v36
	v_fmac_f32_e32 v145, v38, v38
	v_add_f32_e32 v144, v144, v145
	v_mul_f32_e32 v145, v33, v33
	v_mul_f32_e32 v146, v35, v35
	v_fmac_f32_e32 v145, v32, v32
	v_fmac_f32_e32 v146, v34, v34
	v_add_f32_e32 v145, v145, v146
	v_add_f32_e32 v144, v144, v145
	v_mul_f32_e32 v145, v13, v13
	v_mul_f32_e32 v146, v15, v15
	v_fmac_f32_e32 v145, v12, v12
	v_fmac_f32_e32 v146, v14, v14
	v_add_f32_e32 v145, v145, v146
	v_add_f32_e32 v144, v144, v145
	v_mul_f32_e32 v145, v9, v9
	v_mul_f32_e32 v146, v11, v11
	v_fmac_f32_e32 v145, v8, v8
	v_fmac_f32_e32 v146, v10, v10
	v_add_f32_e32 v145, v145, v146
	v_add_f32_e32 v144, v144, v145
	v_mov_b32_e32 v145, v144
	s_nop 1
	v_permlane16_swap_b32_e32 v144, v145
	v_add_f32_e32 v144, v144, v145
	v_mov_b32_e32 v145, v144
	s_nop 1
	v_permlane32_swap_b32_e32 v144, v145
	v_add_f32_e32 v144, v144, v145
	v_fmamk_f32 v144, v144, 0x3c800000, v225
	v_mul_f32_e32 v145, 0x4b800000, v144
	v_cmp_gt_f32_e32 vcc, s93, v144
	s_nop 1
	v_cndmask_b32_e32 v144, v144, v145, vcc
	v_rsq_f32_e32 v144, v144
	s_nop 0
	v_mul_f32_e32 v145, 0x45800000, v144
	v_cndmask_b32_e32 v152, v144, v145, vcc
	v_pk_mul_f32 v[144:145], v[36:37], v[152:153] op_sel_hi:[1,0]
	v_pk_mul_f32 v[146:147], v[38:39], v[152:153] op_sel_hi:[1,0]
	v_pk_mul_f32 v[156:157], v[140:141], v[144:145]
	v_pk_mul_f32 v[158:159], v[142:143], v[146:147]
	v_pk_mul_f32 v[144:145], v[32:33], v[152:153] op_sel_hi:[1,0]
	v_pk_mul_f32 v[146:147], v[34:35], v[152:153] op_sel_hi:[1,0]
	v_pk_mul_f32 v[148:149], v[12:13], v[152:153] op_sel_hi:[1,0]
	v_pk_mul_f32 v[150:151], v[14:15], v[152:153] op_sel_hi:[1,0]
	v_pk_mul_f32 v[186:187], v[8:9], v[152:153] op_sel_hi:[1,0]
	v_pk_mul_f32 v[152:153], v[10:11], v[152:153] op_sel_hi:[1,0]
	v_pk_mul_f32 v[146:147], v[138:139], v[146:147]
	v_pk_mul_f32 v[144:145], v[136:137], v[144:145]
	v_pk_mul_f32 v[150:151], v[134:135], v[150:151]
	v_pk_mul_f32 v[148:149], v[132:133], v[148:149]
	v_pk_mul_f32 v[154:155], v[130:131], v[152:153]
	v_pk_mul_f32 v[152:153], v[128:129], v[186:187]
	s_and_b64 vcc, exec, s[6:7]
	v_add_u32_e32 v186, 0xa0, v180
	s_cbranch_vccnz .LBB0_426
	v_lshlrev_b32_e32 v168, 1, v186
	v_and_b32_e32 v168, 0xf80, v168
	v_lshl_add_u64 v[188:189], v[184:185], 0, v[168:169]
	global_load_dwordx4 v[194:197], v[188:189], off offset:16
	global_load_dwordx4 v[198:201], v[188:189], off
	v_mov_b32_e32 v191, v169
	v_lshl_add_u64 v[190:191], v[184:185], 0, v[190:191]
	global_load_dwordx4 v[236:239], v[190:191], off offset:16
	global_load_dwordx4 v[240:243], v[190:191], off
	s_waitcnt vmcnt(2)
	v_mul_f32_e32 v204, v146, v195
	v_mov_b32_e32 v188, v198
	v_mov_b32_e32 v189, v200
	v_mov_b32_e32 v200, v199
	v_mul_f32_e32 v214, v146, v194
	v_mov_b32_e32 v146, v159
	v_pk_mul_f32 v[198:199], v[144:145], v[200:201]
	v_pk_mul_f32 v[144:145], v[144:145], v[188:189]
	v_mul_f32_e32 v202, v158, v194
	v_mul_f32_e32 v216, v158, v195
	v_pk_mul_f32 v[194:195], v[146:147], v[196:197]
	v_mov_b32_e32 v158, v147
	v_mov_b32_e32 v203, v194
	v_mov_b32_e32 v205, v195
	v_pk_fma_f32 v[194:195], v[156:157], v[188:189], v[198:199] neg_lo:[0,0,1] neg_hi:[0,0,1]
	v_pk_mul_f32 v[146:147], v[158:159], v[196:197]
	v_pk_fma_f32 v[144:145], v[156:157], v[200:201], v[144:145]
	v_pk_add_f32 v[188:189], v[202:203], v[204:205] neg_lo:[0,1] neg_hi:[0,1]
	v_mov_b32_e32 v217, v147
	v_mov_b32_e32 v215, v146
	v_pk_add_f32 v[146:147], v[216:217], v[214:215]
	s_waitcnt vmcnt(0)
	v_mov_b64 v[156:157], v[236:237]
	v_mov_b64 v[158:159], v[238:239]
	v_mov_b64 v[196:197], v[240:241]
	v_mov_b64 v[198:199], v[242:243]
	v_mul_f32_e32 v200, v150, v156
	v_mul_f32_e32 v202, v154, v157
	v_mul_f32_e32 v156, v154, v156
	v_mov_b32_e32 v154, v151
	v_mov_b32_e32 v191, v198
	v_mov_b32_e32 v198, v197
	v_mul_f32_e32 v204, v150, v157
	v_pk_mul_f32 v[214:215], v[154:155], v[158:159]
	v_mov_b32_e32 v150, v155
	v_mov_b32_e32 v190, v196
	v_pk_mul_f32 v[196:197], v[152:153], v[198:199]
	v_mov_b32_e32 v201, v214
	v_mov_b32_e32 v203, v215
	v_pk_mul_f32 v[150:151], v[150:151], v[158:159]
	v_pk_mul_f32 v[152:153], v[152:153], v[190:191]
	v_pk_fma_f32 v[190:191], v[148:149], v[190:191], v[196:197] neg_lo:[0,0,1] neg_hi:[0,0,1]
	v_pk_add_f32 v[196:197], v[200:201], v[202:203] neg_lo:[0,1] neg_hi:[0,1]
	v_mov_b32_e32 v205, v151
	v_mov_b32_e32 v157, v150
	v_pk_fma_f32 v[152:153], v[148:149], v[198:199], v[152:153]
	v_pk_add_f32 v[154:155], v[204:205], v[156:157]
	v_mov_b32_e32 v148, v190
	v_mov_b32_e32 v149, v191
	v_mov_b32_e32 v150, v196
	v_mov_b32_e32 v151, v197
	v_mov_b32_e32 v156, v194
	v_mov_b32_e32 v157, v195
	v_mov_b32_e32 v158, v188
	v_mov_b32_e32 v159, v189

.LBB0_435:
	v_mul_f32_e32 v144, v21, v21
	v_mul_f32_e32 v145, v23, v23
	v_fmac_f32_e32 v144, v20, v20
	v_fmac_f32_e32 v145, v22, v22
	v_add_f32_e32 v144, v144, v145
	v_mul_f32_e32 v145, v17, v17
	v_mul_f32_e32 v146, v19, v19
	v_fmac_f32_e32 v145, v16, v16
	v_fmac_f32_e32 v146, v18, v18
	v_add_f32_e32 v145, v145, v146
	v_add_f32_e32 v144, v144, v145
	v_mul_f32_e32 v145, v5, v5
	v_mul_f32_e32 v146, v7, v7
	v_fmac_f32_e32 v145, v4, v4
	v_fmac_f32_e32 v146, v6, v6
	v_add_f32_e32 v145, v145, v146
	v_add_f32_e32 v144, v144, v145
	v_mul_f32_e32 v145, v1, v1
	v_mul_f32_e32 v146, v3, v3
	v_fmac_f32_e32 v145, v0, v0
	v_fmac_f32_e32 v146, v2, v2
	v_add_f32_e32 v145, v145, v146
	v_add_f32_e32 v144, v144, v145
	v_mov_b32_e32 v145, v144
	s_nop 1
	v_permlane16_swap_b32_e32 v144, v145
	v_add_f32_e32 v144, v144, v145
	v_mov_b32_e32 v145, v144
	s_nop 1
	v_permlane32_swap_b32_e32 v144, v145
	v_add_f32_e32 v144, v144, v145
	v_fmamk_f32 v144, v144, 0x3c800000, v225
	v_mul_f32_e32 v145, 0x4b800000, v144
	v_cmp_gt_f32_e32 vcc, s93, v144
	s_nop 1
	v_cndmask_b32_e32 v144, v144, v145, vcc
	v_rsq_f32_e32 v144, v144
	s_nop 0
	v_mul_f32_e32 v145, 0x45800000, v144
	v_cndmask_b32_e32 v144, v144, v145, vcc
	v_pk_mul_f32 v[146:147], v[20:21], v[144:145] op_sel_hi:[1,0]
	v_pk_mul_f32 v[148:149], v[22:23], v[144:145] op_sel_hi:[1,0]
	v_pk_mul_f32 v[140:141], v[140:141], v[146:147]
	v_pk_mul_f32 v[146:147], v[16:17], v[144:145] op_sel_hi:[1,0]
	v_pk_mul_f32 v[142:143], v[142:143], v[148:149]
	v_pk_mul_f32 v[148:149], v[18:19], v[144:145] op_sel_hi:[1,0]
	v_pk_mul_f32 v[136:137], v[136:137], v[146:147]
	v_pk_mul_f32 v[146:147], v[4:5], v[144:145] op_sel_hi:[1,0]
	v_pk_mul_f32 v[138:139], v[138:139], v[148:149]
	v_pk_mul_f32 v[148:149], v[6:7], v[144:145] op_sel_hi:[1,0]
	v_pk_mul_f32 v[132:133], v[132:133], v[146:147]
	v_pk_mul_f32 v[146:147], v[0:1], v[144:145] op_sel_hi:[1,0]
	v_pk_mul_f32 v[144:145], v[2:3], v[144:145] op_sel_hi:[1,0]
	v_pk_mul_f32 v[134:135], v[134:135], v[148:149]
	v_pk_mul_f32 v[130:131], v[130:131], v[144:145]
	v_pk_mul_f32 v[128:129], v[128:129], v[146:147]
	s_and_b64 vcc, exec, s[6:7]
	v_add_u32_e32 v144, 0xb0, v180
	s_cbranch_vccnz .LBB0_437
	v_lshlrev_b32_e32 v145, 1, v144
	v_and_b32_e32 v168, 0xf80, v145
	v_lshl_add_u64 v[146:147], v[184:185], 0, v[168:169]
	global_load_dwordx4 v[148:151], v[146:147], off offset:16
	global_load_dwordx4 v[152:155], v[146:147], off
	v_mov_b32_e32 v193, v169
	v_lshl_add_u64 v[252:253], v[184:185], 0, v[192:193]
	global_load_dwordx4 v[236:239], v[252:253], off offset:16
	global_load_dwordx4 v[240:243], v[252:253], off
	s_waitcnt vmcnt(2)
	v_mul_f32_e32 v156, v142, v148
	v_mov_b32_e32 v146, v152
	v_mov_b32_e32 v147, v154
	v_mov_b32_e32 v154, v153
	v_mul_f32_e32 v158, v138, v149
	v_mul_f32_e32 v186, v138, v148
	v_mul_f32_e32 v188, v142, v149
	v_mov_b32_e32 v138, v143
	v_mov_b32_e32 v142, v139
	v_pk_mul_f32 v[152:153], v[136:137], v[154:155]
	v_pk_mul_f32 v[136:137], v[136:137], v[146:147]
	v_pk_mul_f32 v[148:149], v[138:139], v[150:151]
	v_pk_mul_f32 v[138:139], v[142:143], v[150:151]
	v_mov_b32_e32 v157, v148
	v_mov_b32_e32 v159, v149
	v_pk_fma_f32 v[148:149], v[140:141], v[146:147], v[152:153] neg_lo:[0,0,1] neg_hi:[0,0,1]
	v_pk_fma_f32 v[136:137], v[140:141], v[154:155], v[136:137]
	v_pk_add_f32 v[146:147], v[156:157], v[158:159] neg_lo:[0,1] neg_hi:[0,1]
	v_mov_b32_e32 v189, v139
	v_mov_b32_e32 v187, v138
	v_pk_add_f32 v[138:139], v[188:189], v[186:187]
	s_waitcnt vmcnt(0)
	v_mov_b64 v[140:141], v[236:237]
	v_mov_b64 v[142:143], v[238:239]
	v_mov_b64 v[150:151], v[240:241]
	v_mov_b64 v[152:153], v[242:243]
	v_mul_f32_e32 v156, v134, v140
	v_mul_f32_e32 v158, v130, v141
	v_mul_f32_e32 v140, v130, v140
	v_mov_b32_e32 v130, v135
	v_mov_b32_e32 v155, v152
	v_mov_b32_e32 v152, v151
	v_mul_f32_e32 v184, v134, v141
	v_pk_mul_f32 v[186:187], v[130:131], v[142:143]
	v_mov_b32_e32 v134, v131
	v_mov_b32_e32 v154, v150
	v_pk_mul_f32 v[150:151], v[128:129], v[152:153]
	v_mov_b32_e32 v157, v186
	v_mov_b32_e32 v159, v187
	v_pk_mul_f32 v[130:131], v[134:135], v[142:143]
	v_pk_mul_f32 v[128:129], v[128:129], v[154:155]
	v_pk_fma_f32 v[150:151], v[132:133], v[154:155], v[150:151] neg_lo:[0,0,1] neg_hi:[0,0,1]
	v_pk_add_f32 v[154:155], v[156:157], v[158:159] neg_lo:[0,1] neg_hi:[0,1]
	v_mov_b32_e32 v185, v131
	v_mov_b32_e32 v141, v130
	v_pk_fma_f32 v[128:129], v[132:133], v[152:153], v[128:129]
	v_pk_add_f32 v[130:131], v[184:185], v[140:141]
	v_mov_b32_e32 v132, v150
	v_mov_b32_e32 v133, v151
	v_mov_b32_e32 v134, v154
	v_mov_b32_e32 v135, v155
	v_mov_b32_e32 v140, v148
	v_mov_b32_e32 v141, v149
	v_mov_b32_e32 v142, v146
	v_mov_b32_e32 v143, v147
